# attention: defer cross-half row-sum reduction to pass end (per-lane partial l, fma update), on top of permlane-free P packing
# speedup vs baseline: 1.0044x; 1.0044x over previous
; DI void finishSM(f32x16& p0, f32x16& p1, float alpha, float& l_reg, bf16x8& pa0, bf16x8& pa1, bf16x8& pa2, bf16x8& pa3) {
; #pragma unroll
;     for (int r = 0; r < 16; ++r) p1[r] = __builtin_amdgcn_exp2f(p1[r]);
;     float ps = 0;
; #pragma unroll
;     for (int r = 0; r < 16; ++r) ps += p0[r];
; #pragma unroll
;     for (int r = 0; r < 16; ++r) ps += p1[r];
;     { auto rr = __builtin_amdgcn_permlane32_swap(__float_as_uint(ps), __float_as_uint(ps), false, false);
;       ps = __uint_as_float(rr[0]) + __uint_as_float(rr[1]); }
;     l_reg = l_reg * alpha + ps;
;     ...
;     PK4(p0, 0, pa0); PK4(p0, 8, pa1); PK4(p1, 0, pa2); PK4(p1, 8, pa3);
;     ...
; }
; DI void qkt(f32x16& p0, f32x16& p1, const char* Ks, const bf16x8* qr, const f32x16& negm, int r32, int hi) {
;     { const bf16x8 b0 = *reinterpret_cast<const bf16x8*>(Ks + KSWZ(r32, hi * 16));
;       const bf16x8 b1 = *reinterpret_cast<const bf16x8*>(Ks + KSWZ(32 + r32, hi * 16));
;       p0 = __builtin_amdgcn_mfma_f32_32x32x16_bf16(b0, qr[0], negm, 0, 0, 0);
;       p1 = __builtin_amdgcn_mfma_f32_32x32x16_bf16(b1, qr[0], negm, 0, 0, 0); }
; #pragma unroll
;     for (int d0 = 1; d0 < 4; ++d0) { const int cb = (d0 * 16 + hi * 8) * 2;
;         const bf16x8 b0 = *reinterpret_cast<const bf16x8*>(Ks + KSWZ(r32, cb));
;         const bf16x8 b1 = *reinterpret_cast<const bf16x8*>(Ks + KSWZ(32 + r32, cb));
;         p0 = __builtin_amdgcn_mfma_f32_32x32x16_bf16(b0, qr[d0], p0, 0, 0, 0);
;         p1 = __builtin_amdgcn_mfma_f32_32x32x16_bf16(b1, qr[d0], p1, 0, 0, 0); }
; }
; DI int v_st(int k, int c) { const int kk = (k & ~0xC) | ((k & 4) << 1) | ((k & 8) >> 1); return ((kk >> 3) * 4 + (c >> 5)) * 512 + ((kk & 7) * 32 + (c & 31)) * 2; }
; DI int v_rd_base(int lane) { return ((lane & 3) << 3) | (((lane >> 2) & 3) << 6) | (((lane >> 4) & 1) << 5) | (((lane >> 5) & 1) << 8); }
; template <int OFF> DI s16x4 tr_read(int vb) { s16x4 r; asm volatile("ds_read_b64_tr_b16 %0, %1 offset:%2" : "=&v"(r) : "v"(vb), "i"(OFF) : "memory"); return r; }
; template <int D0> DI void pv_one(f32x16& od, int vb, bf16x8 pa0, bf16x8 pa1, bf16x8 pa2, bf16x8 pa3) {
;     const s16x4 l0 = tr_read<v_rd_off(D0, 0, 0)>(vb), h0 = tr_read<v_rd_off(D0, 0, 1)>(vb), l1 = tr_read<v_rd_off(D0, 1, 0)>(vb), h1 = tr_read<v_rd_off(D0, 1, 1)>(vb);
.LBB0_1038:
	ds_read_b128 v[80:83], v217 offset:40960
	ds_read_b128 v[84:87], v217 offset:45056
	v_exp_f32_e32 v88, v96
	v_exp_f32_e32 v89, v97
	v_exp_f32_e32 v90, v98
	s_waitcnt lgkmcnt(1)
	v_mfma_f32_32x32x16_bf16 v[128:143], v[80:83], v[148:151], v[64:79]
	v_exp_f32_e32 v91, v99
	v_exp_f32_e32 v92, v100
	v_exp_f32_e32 v93, v101
	v_exp_f32_e32 v94, v102
	v_exp_f32_e32 v95, v103
	v_exp_f32_e32 v96, v104
	v_exp_f32_e32 v97, v105
	s_waitcnt lgkmcnt(0)
	v_mfma_f32_32x32x16_bf16 v[112:127], v[84:87], v[148:151], v[64:79]
	ds_read_b128 v[80:83], v218 offset:40960
	ds_read_b128 v[84:87], v218 offset:45056
	v_exp_f32_e32 v98, v106
	v_exp_f32_e32 v99, v107
	v_exp_f32_e32 v100, v108
	v_exp_f32_e32 v101, v109
	v_exp_f32_e32 v102, v110
	v_exp_f32_e32 v103, v111
	s_waitcnt lgkmcnt(1)
	v_mfma_f32_32x32x16_bf16 v[128:143], v[80:83], v[144:147], v[128:143]
	s_waitcnt lgkmcnt(0)
	v_mfma_f32_32x32x16_bf16 v[112:127], v[84:87], v[144:147], v[112:127]
	ds_read_b128 v[80:83], v219 offset:40960
	ds_read_b128 v[84:87], v219 offset:45056
	s_waitcnt lgkmcnt(1)
	v_mfma_f32_32x32x16_bf16 v[128:143], v[80:83], v[152:155], v[128:143]
	s_waitcnt lgkmcnt(0)
	v_mfma_f32_32x32x16_bf16 v[112:127], v[84:87], v[152:155], v[112:127]
	ds_read_b128 v[80:83], v216 offset:40960
	ds_read_b128 v[84:87], v216 offset:45056
	s_waitcnt lgkmcnt(1)
	v_mfma_f32_32x32x16_bf16 v[128:143], v[80:83], v[156:159], v[128:143]
	v_add_f32_e32 v80, v209, v207
	v_add_f32_e32 v80, v183, v80
	v_add_f32_e32 v80, v208, v80
	v_add_f32_e32 v80, v181, v80
	v_add_f32_e32 v80, v206, v80
	v_add_f32_e32 v80, v180, v80
	v_add_f32_e32 v80, v182, v80
	v_add_f32_e32 v80, v173, v80
	v_add_f32_e32 v80, v175, v80
	v_add_f32_e32 v80, v172, v80
	v_add_f32_e32 v80, v174, v80
	v_add_f32_e32 v80, v177, v80
	v_add_f32_e32 v80, v179, v80
	v_add_f32_e32 v80, v176, v80
	v_add_f32_e32 v80, v178, v80
	v_add_f32_e32 v80, v88, v80
	v_add_f32_e32 v80, v89, v80
	v_add_f32_e32 v80, v90, v80
	v_add_f32_e32 v80, v91, v80
	v_add_f32_e32 v80, v92, v80
	v_add_f32_e32 v80, v93, v80
	v_add_f32_e32 v80, v94, v80
	v_add_f32_e32 v80, v95, v80
	v_add_f32_e32 v80, v96, v80
	v_add_f32_e32 v80, v97, v80
	s_waitcnt lgkmcnt(0)
	v_mfma_f32_32x32x16_bf16 v[112:127], v[84:87], v[156:159], v[112:127]
	v_add_f32_e32 v80, v98, v80
	v_add_f32_e32 v80, v99, v80
	v_add_f32_e32 v80, v100, v80
	v_add_f32_e32 v80, v101, v80
	v_add_f32_e32 v80, v102, v80
	v_add_f32_e32 v222, v103, v80
	v_cvt_pk_bf16_f32 v80, v207, v209
	v_cvt_pk_bf16_f32 v81, v183, v208
	v_cvt_pk_bf16_f32 v82, v181, v206
	v_cvt_pk_bf16_f32 v83, v180, v182
	v_cvt_pk_bf16_f32 v84, v173, v175
	v_cvt_pk_bf16_f32 v85, v172, v174
	v_cvt_pk_bf16_f32 v86, v177, v179
	v_cvt_pk_bf16_f32 v87, v176, v178
	v_cvt_pk_bf16_f32 v88, v88, v89
	v_cvt_pk_bf16_f32 v89, v90, v91
	v_cvt_pk_bf16_f32 v90, v92, v93
	v_cvt_pk_bf16_f32 v91, v94, v95
	v_cvt_pk_bf16_f32 v92, v96, v97
	v_cvt_pk_bf16_f32 v93, v98, v99
	v_cvt_pk_bf16_f32 v94, v100, v101
	v_cvt_pk_bf16_f32 v95, v102, v103
	global_load_dwordx4 v[172:175], v203, s[98:99]
	global_load_dwordx4 v[176:179], v204, s[98:99]
	global_load_dwordx4 v[180:183], v202, s[100:101]
	s_add_u32 s98, s98, 0x20000
	s_addc_u32 s99, s99, 0
	s_add_u32 s100, s100, 0x20000
	s_addc_u32 s101, s101, 0
	ds_read_b64_tr_b16 v[96:97], v220 offset:0
	ds_read_b64_tr_b16 v[98:99], v220 offset:0x100
	ds_read_b64_tr_b16 v[100:101], v220 offset:0x1000
	ds_read_b64_tr_b16 v[102:103], v220 offset:0x1100
	ds_read_b64_tr_b16 v[104:105], v220 offset:0x2000
	ds_read_b64_tr_b16 v[106:107], v220 offset:0x2100
	ds_read_b64_tr_b16 v[108:109], v220 offset:0x3000
	ds_read_b64_tr_b16 v[110:111], v220 offset:0x3100
	s_waitcnt lgkmcnt(0)
	s_nop 0
	v_mfma_f32_32x32x16_bf16 v[48:63], v[80:83], v[96:99], v[48:63]
	ds_read_b64_tr_b16 v[96:97], v220 offset:0x200
	ds_read_b64_tr_b16 v[98:99], v220 offset:0x300
	v_mfma_f32_32x32x16_bf16 v[48:63], v[84:87], v[100:103], v[48:63]
	ds_read_b64_tr_b16 v[100:101], v220 offset:0x1200
	ds_read_b64_tr_b16 v[102:103], v220 offset:0x1300
	v_mfma_f32_32x32x16_bf16 v[48:63], v[88:91], v[104:107], v[48:63]
	ds_read_b64_tr_b16 v[104:105], v220 offset:0x2200
	ds_read_b64_tr_b16 v[106:107], v220 offset:0x2300
	v_mfma_f32_32x32x16_bf16 v[48:63], v[92:95], v[108:111], v[48:63]
	ds_read_b64_tr_b16 v[108:109], v220 offset:0x3200
	ds_read_b64_tr_b16 v[110:111], v220 offset:0x3300
	s_waitcnt lgkmcnt(0)
	v_mfma_f32_32x32x16_bf16 v[32:47], v[80:83], v[96:99], v[32:47]
	ds_read_b64_tr_b16 v[96:97], v220 offset:0x400
	ds_read_b64_tr_b16 v[98:99], v220 offset:0x500
	v_mfma_f32_32x32x16_bf16 v[32:47], v[84:87], v[100:103], v[32:47]
	ds_read_b64_tr_b16 v[100:101], v220 offset:0x1400
	ds_read_b64_tr_b16 v[102:103], v220 offset:0x1500
	v_mfma_f32_32x32x16_bf16 v[32:47], v[88:91], v[104:107], v[32:47]
	ds_read_b64_tr_b16 v[104:105], v220 offset:0x2400
	ds_read_b64_tr_b16 v[106:107], v220 offset:0x2500
	v_mfma_f32_32x32x16_bf16 v[32:47], v[92:95], v[108:111], v[32:47]
	ds_read_b64_tr_b16 v[108:109], v220 offset:0x3400
	ds_read_b64_tr_b16 v[110:111], v220 offset:0x3500
	s_waitcnt lgkmcnt(0)
	v_mfma_f32_32x32x16_bf16 v[16:31], v[80:83], v[96:99], v[16:31]
	ds_read_b64_tr_b16 v[96:97], v220 offset:0x600
	ds_read_b64_tr_b16 v[98:99], v220 offset:0x700
	v_mfma_f32_32x32x16_bf16 v[16:31], v[84:87], v[100:103], v[16:31]
	ds_read_b64_tr_b16 v[100:101], v220 offset:0x1600
	ds_read_b64_tr_b16 v[102:103], v220 offset:0x1700
	v_mfma_f32_32x32x16_bf16 v[16:31], v[88:91], v[104:107], v[16:31]
	ds_read_b64_tr_b16 v[104:105], v220 offset:0x2600
	ds_read_b64_tr_b16 v[106:107], v220 offset:0x2700
	v_mfma_f32_32x32x16_bf16 v[16:31], v[92:95], v[108:111], v[16:31]
	ds_read_b64_tr_b16 v[108:109], v220 offset:0x3600
	ds_read_b64_tr_b16 v[110:111], v220 offset:0x3700
	s_waitcnt lgkmcnt(0)
	v_mfma_f32_32x32x16_bf16 v[0:15], v[80:83], v[96:99], v[0:15]
	v_max_f32_e32 v80, v128, v129
	v_max3_f32 v80, v80, v130, v131
	v_max3_f32 v80, v80, v132, v133
	v_max3_f32 v80, v80, v134, v135
	v_max3_f32 v80, v80, v136, v137
	v_mfma_f32_32x32x16_bf16 v[0:15], v[84:87], v[100:103], v[0:15]
	v_max3_f32 v80, v80, v138, v139
	v_max3_f32 v80, v80, v140, v141
	v_max3_f32 v80, v80, v142, v143
	v_max3_f32 v80, v80, v112, v113
	v_max3_f32 v80, v80, v114, v115
	v_max3_f32 v80, v80, v116, v117
	v_max3_f32 v80, v80, v118, v119
	v_mfma_f32_32x32x16_bf16 v[0:15], v[88:91], v[104:107], v[0:15]
	v_max3_f32 v80, v80, v120, v121
	v_max3_f32 v80, v80, v122, v123
	v_max3_f32 v80, v80, v124, v125
	v_max3_f32 v80, v80, v126, v127
	v_mov_b32_e32 v81, v80
	s_nop 1
	v_permlane32_swap_b32_e32 v80, v81
	v_mfma_f32_32x32x16_bf16 v[0:15], v[92:95], v[108:111], v[0:15]
	v_max_f32_e32 v80, v80, v81
	v_cmp_ngt_f32_e32 vcc, s83, v200
	v_cmp_ge_f32_e64 s[8:9], s63, v80
	s_and_b64 s[4:5], vcc, s[8:9]
	s_cmp_eq_u64 s[4:5], exec
	s_cbranch_scc0 .LBB0_1057
	v_mov_b32_e32 v224, 1.0

; DI void partialSM(f32x16& p0, f32x16& p1, float& m_reg, f32x16& negm, float& alpha) {
;     ...
;     for (int r = 0; r < 16; ++r) p0[r] = __builtin_amdgcn_exp2f(p0[r]);
; }
; DI void finishSM(f32x16& p0, f32x16& p1, float alpha, float& l_reg, bf16x8& pa0, bf16x8& pa1, bf16x8& pa2, bf16x8& pa3) {
; #pragma unroll
;     for (int r = 0; r < 16; ++r) p1[r] = __builtin_amdgcn_exp2f(p1[r]);
;     float ps = 0;
; #pragma unroll
;     for (int r = 0; r < 16; ++r) ps += p0[r];
; #pragma unroll
;     for (int r = 0; r < 16; ++r) ps += p1[r];
;     { auto rr = __builtin_amdgcn_permlane32_swap(__float_as_uint(ps), __float_as_uint(ps), false, false);
;       ps = __uint_as_float(rr[0]) + __uint_as_float(rr[1]); }
;     l_reg = l_reg * alpha + ps;
;     ...
;     PK4(p0, 0, pa0); PK4(p0, 8, pa1); PK4(p1, 0, pa2); PK4(p1, 8, pa3);
;     ...
; }
; DI void qkt(f32x16& p0, f32x16& p1, const char* Ks, const bf16x8* qr, const f32x16& negm, int r32, int hi) {
;     { const bf16x8 b0 = *reinterpret_cast<const bf16x8*>(Ks + KSWZ(r32, hi * 16));
;       const bf16x8 b1 = *reinterpret_cast<const bf16x8*>(Ks + KSWZ(32 + r32, hi * 16));
;       p0 = __builtin_amdgcn_mfma_f32_32x32x16_bf16(b0, qr[0], negm, 0, 0, 0);
;       p1 = __builtin_amdgcn_mfma_f32_32x32x16_bf16(b1, qr[0], negm, 0, 0, 0); }
; #pragma unroll
;     for (int d0 = 1; d0 < 4; ++d0) { const int cb = (d0 * 16 + hi * 8) * 2;
;         const bf16x8 b0 = *reinterpret_cast<const bf16x8*>(Ks + KSWZ(r32, cb));
;         const bf16x8 b1 = *reinterpret_cast<const bf16x8*>(Ks + KSWZ(32 + r32, cb));
;         p0 = __builtin_amdgcn_mfma_f32_32x32x16_bf16(b0, qr[d0], p0, 0, 0, 0);
;         p1 = __builtin_amdgcn_mfma_f32_32x32x16_bf16(b1, qr[d0], p1, 0, 0, 0); }
; }
.LBB0_1044:
	v_exp_f32_e32 v246, v128
	v_exp_f32_e32 v248, v129
	v_exp_f32_e32 v244, v130
	v_exp_f32_e32 v247, v131
	v_exp_f32_e32 v236, v132
	v_exp_f32_e32 v245, v133
	v_exp_f32_e32 v235, v134
	v_exp_f32_e32 v237, v135
	v_exp_f32_e32 v232, v136
	v_exp_f32_e32 v234, v137
	v_exp_f32_e32 v230, v138
	v_exp_f32_e32 v233, v139
	v_exp_f32_e32 v228, v140
	v_exp_f32_e32 v231, v141
	v_exp_f32_e32 v227, v142
	v_exp_f32_e32 v229, v143
	s_waitcnt lgkmcnt(0)
	s_barrier
	ds_read_b128 v[96:99], v217 offset:32768
	ds_read_b128 v[250:253], v217 offset:36864
	v_exp_f32_e32 v249, v120
	v_exp_f32_e32 v254, v121
	v_exp_f32_e32 v186, v122
	s_waitcnt lgkmcnt(1)
	v_mfma_f32_32x32x16_bf16 v[128:143], v[96:99], v[148:151], v[64:79]
	v_exp_f32_e32 v187, v123
	v_exp_f32_e32 v188, v124
	v_exp_f32_e32 v189, v125
	v_exp_f32_e32 v194, v126
	v_exp_f32_e32 v127, v127
	s_waitcnt lgkmcnt(0)
	v_mfma_f32_32x32x16_bf16 v[96:111], v[250:253], v[148:151], v[64:79]
	ds_read_b128 v[250:253], v218 offset:32768
	ds_read_b128 v[238:241], v218 offset:36864
	s_waitcnt lgkmcnt(1)
	v_mfma_f32_32x32x16_bf16 v[128:143], v[250:253], v[144:147], v[128:143]
	s_waitcnt lgkmcnt(0)
	v_mfma_f32_32x32x16_bf16 v[96:111], v[238:241], v[144:147], v[96:111]
	ds_read_b128 v[238:241], v219 offset:32768
	ds_read_b128 v[250:253], v219 offset:36864
	s_waitcnt lgkmcnt(1)
	v_mfma_f32_32x32x16_bf16 v[128:143], v[238:241], v[152:155], v[128:143]
	s_waitcnt lgkmcnt(0)
	v_mfma_f32_32x32x16_bf16 v[96:111], v[250:253], v[152:155], v[96:111]
	ds_read_b128 v[238:241], v216 offset:32768
	ds_read_b128 v[250:253], v216 offset:36864
	s_waitcnt lgkmcnt(1)
	v_mfma_f32_32x32x16_bf16 v[128:143], v[238:241], v[156:159], v[128:143]
	v_exp_f32_e32 v238, v112
	v_add_f32_e32 v112, v248, v246
	v_add_f32_e32 v112, v244, v112
	v_add_f32_e32 v112, v247, v112
	v_add_f32_e32 v112, v236, v112
	v_add_f32_e32 v112, v245, v112
	v_add_f32_e32 v112, v235, v112
	v_add_f32_e32 v112, v237, v112
	v_add_f32_e32 v112, v232, v112
	v_add_f32_e32 v112, v234, v112
	v_add_f32_e32 v112, v230, v112
	v_add_f32_e32 v112, v233, v112
	v_add_f32_e32 v112, v228, v112
	v_exp_f32_e32 v239, v113
	v_add_f32_e32 v112, v231, v112
	v_exp_f32_e32 v240, v114
	v_add_f32_e32 v112, v227, v112
	v_exp_f32_e32 v241, v115
	v_add_f32_e32 v112, v229, v112
	s_waitcnt lgkmcnt(0)
	v_mfma_f32_32x32x16_bf16 v[96:111], v[250:253], v[156:159], v[96:111]
	v_exp_f32_e32 v250, v116
	v_add_f32_e32 v112, v238, v112
	v_exp_f32_e32 v251, v117
	v_add_f32_e32 v112, v239, v112
	v_exp_f32_e32 v252, v118
	v_add_f32_e32 v112, v240, v112
	v_exp_f32_e32 v253, v119
	v_add_f32_e32 v112, v241, v112
	v_add_f32_e32 v112, v250, v112
	v_add_f32_e32 v112, v251, v112
	v_add_f32_e32 v112, v252, v112
	v_add_f32_e32 v112, v253, v112
	v_add_f32_e32 v112, v249, v112
	v_add_f32_e32 v112, v254, v112
	v_add_f32_e32 v112, v186, v112
	v_add_f32_e32 v112, v187, v112
	v_add_f32_e32 v112, v188, v112
	v_add_f32_e32 v112, v189, v112
	v_add_f32_e32 v112, v194, v112
	v_add_f32_e32 v225, v127, v112
	v_cvt_pk_bf16_f32 v112, v246, v248
	v_cvt_pk_bf16_f32 v113, v244, v247
	v_cvt_pk_bf16_f32 v114, v236, v245
	v_cvt_pk_bf16_f32 v115, v235, v237
	v_cvt_pk_bf16_f32 v116, v232, v234
	v_cvt_pk_bf16_f32 v117, v230, v233
	v_cvt_pk_bf16_f32 v118, v228, v231
	v_cvt_pk_bf16_f32 v119, v227, v229
	v_cvt_pk_bf16_f32 v120, v238, v239
	v_cvt_pk_bf16_f32 v121, v240, v241
	v_cvt_pk_bf16_f32 v122, v250, v251
	v_cvt_pk_bf16_f32 v123, v252, v253
	v_cvt_pk_bf16_f32 v124, v249, v254
	v_cvt_pk_bf16_f32 v125, v186, v187
	v_cvt_pk_bf16_f32 v126, v188, v189
	v_cvt_pk_bf16_f32 v127, v194, v127
	s_cmp_ge_u32 s2, s22
	s_cselect_b64 s[4:5], -1, 0
	s_and_b64 vcc, exec, s[4:5]
	s_cbranch_vccnz .LBB0_1046
	global_load_dwordx4 v[160:163], v203, s[98:99]
	global_load_dwordx4 v[164:167], v204, s[98:99]
	global_load_dwordx4 v[168:171], v202, s[100:101]

; #define SBAR() __builtin_amdgcn_sched_barrier(0)
; #define SLOADA(k0) do { vsA0 = *reinterpret_cast<const bf16x8*>(&Vh[(size_t)((k0) + sr) * LDQ + sc]); vsA1 = *reinterpret_cast<const bf16x8*>(&Vh[(size_t)((k0) + 32 + sr) * LDQ + sc]); \
;     ksA = *reinterpret_cast<const bf16x8*>(&Kh[(size_t)((k0) + kr) * LDQ + kc]); } while (0)
; #define SLOADB(k0) do { vsB0 = *reinterpret_cast<const bf16x8*>(&Vh[(size_t)((k0) + sr) * LDQ + sc]); vsB1 = *reinterpret_cast<const bf16x8*>(&Vh[(size_t)((k0) + 32 + sr) * LDQ + sc]); \
;     ksB = *reinterpret_cast<const bf16x8*>(&Kh[(size_t)((k0) + kr) * LDQ + kc]); } while (0)
; DI void partialSM(f32x16& p0, f32x16& p1, float& m_reg, f32x16& negm, float& alpha) {
;     ...
;     for (int r = 0; r < 16; ++r) p0[r] = __builtin_amdgcn_exp2f(p0[r]);
; }
; DI void finishSM(f32x16& p0, f32x16& p1, float alpha, float& l_reg, bf16x8& pa0, bf16x8& pa1, bf16x8& pa2, bf16x8& pa3) {
; #pragma unroll
;     for (int r = 0; r < 16; ++r) p1[r] = __builtin_amdgcn_exp2f(p1[r]);
;     float ps = 0;
; #pragma unroll
;     for (int r = 0; r < 16; ++r) ps += p0[r];
; #pragma unroll
;     for (int r = 0; r < 16; ++r) ps += p1[r];
;     { auto rr = __builtin_amdgcn_permlane32_swap(__float_as_uint(ps), __float_as_uint(ps), false, false);
;       ps = __uint_as_float(rr[0]) + __uint_as_float(rr[1]); }
;     l_reg = l_reg * alpha + ps;
; DI void attn_pass(const bf16_t* __restrict__ Qb, const bf16_t* __restrict__ Kh, const bf16_t* __restrict__ Vh, int seq, char* lds, f32x16 (&o)[4], float& l_out) {
;     ...
;     for (int j = 1; j + 1 < NT; j += 2) {
;         SBAR(); qkt(pB0, pB1, K_lds + SHM_K, qr, negm, r32, hi);
;         finishSM(pA0, pA1, alA, l_reg, pa0, pa1, pa2, pa3); SBAR();
;         SLOADB((j + 2) * KVBLK); SBAR();
;         pv_d0(o, vb0, pa0, pa1, pa2, pa3); partialSM(pB0, pB1, m_reg, negm, alB);
;         __syncthreads(); SWAIT(); SWRITEA(0);
;         RESC(alB); __syncthreads();
;         SBAR(); qkt(pA0, pA1, K_lds, qr, negm, r32, hi);
;         finishSM(pB0, pB1, alB, l_reg, pa0, pa1, pa2, pa3); SBAR();
;         if (j + 3 < NT) SLOADA((j + 3) * KVBLK); SBAR();
;         pv_d0(o, vb0 + SHM_V, pa0, pa1, pa2, pa3); partialSM(pA0, pA1, m_reg, negm, alA);
;         __syncthreads(); if (j + 3 < NT) SWAIT(); else asm volatile("s_waitcnt vmcnt(0)" ::: "memory"); SWRITEB(1);
;         RESC(alA); __syncthreads();
;     }
.LBB0_1055:
	v_exp_f32_e32 v207, v128
	v_exp_f32_e32 v209, v129
	v_exp_f32_e32 v183, v130
	v_exp_f32_e32 v208, v131
	v_exp_f32_e32 v181, v132
	v_exp_f32_e32 v206, v133
	v_exp_f32_e32 v180, v134
	v_exp_f32_e32 v182, v135
	v_exp_f32_e32 v173, v136
	v_exp_f32_e32 v175, v137
	v_exp_f32_e32 v172, v138
	v_exp_f32_e32 v174, v139
	v_exp_f32_e32 v177, v140
	v_exp_f32_e32 v179, v141
	v_exp_f32_e32 v176, v142
	v_exp_f32_e32 v178, v143
	v_fma_f32 v113, v221, v210, v222
	v_fma_f32 v210, v113, v224, v225
	s_add_i32 s2, s2, 2
	s_and_b64 vcc, exec, s[4:5]
	s_waitcnt lgkmcnt(0)
	s_barrier
	s_cbranch_vccnz .LBB0_1059
	v_mov_b32_e32 v221, v112
	s_branch .LBB0_1038

; DI void finishSM(f32x16& p0, f32x16& p1, float alpha, float& l_reg, bf16x8& pa0, bf16x8& pa1, bf16x8& pa2, bf16x8& pa3) {
; #pragma unroll
;     for (int r = 0; r < 16; ++r) p1[r] = __builtin_amdgcn_exp2f(p1[r]);
;     float ps = 0;
; #pragma unroll
;     for (int r = 0; r < 16; ++r) ps += p0[r];
; #pragma unroll
;     for (int r = 0; r < 16; ++r) ps += p1[r];
;     { auto rr = __builtin_amdgcn_permlane32_swap(__float_as_uint(ps), __float_as_uint(ps), false, false);
;       ps = __uint_as_float(rr[0]) + __uint_as_float(rr[1]); }
;     l_reg = l_reg * alpha + ps;
;     ...
;     PK4(p0, 0, pa0); PK4(p0, 8, pa1); PK4(p1, 0, pa2); PK4(p1, 8, pa3);
;     ...
; }
; DI void qkt(f32x16& p0, f32x16& p1, const char* Ks, const bf16x8* qr, const f32x16& negm, int r32, int hi) {
;     { const bf16x8 b0 = *reinterpret_cast<const bf16x8*>(Ks + KSWZ(r32, hi * 16));
;       const bf16x8 b1 = *reinterpret_cast<const bf16x8*>(Ks + KSWZ(32 + r32, hi * 16));
;       p0 = __builtin_amdgcn_mfma_f32_32x32x16_bf16(b0, qr[0], negm, 0, 0, 0);
;       p1 = __builtin_amdgcn_mfma_f32_32x32x16_bf16(b1, qr[0], negm, 0, 0, 0); }
; #pragma unroll
;     for (int d0 = 1; d0 < 4; ++d0) { const int cb = (d0 * 16 + hi * 8) * 2;
;         const bf16x8 b0 = *reinterpret_cast<const bf16x8*>(Ks + KSWZ(r32, cb));
;         const bf16x8 b1 = *reinterpret_cast<const bf16x8*>(Ks + KSWZ(32 + r32, cb));
;         p0 = __builtin_amdgcn_mfma_f32_32x32x16_bf16(b0, qr[d0], p0, 0, 0, 0);
;         p1 = __builtin_amdgcn_mfma_f32_32x32x16_bf16(b1, qr[d0], p1, 0, 0, 0); }
; }
; DI int v_st(int k, int c) { const int kk = (k & ~0xC) | ((k & 4) << 1) | ((k & 8) >> 1); return ((kk >> 3) * 4 + (c >> 5)) * 512 + ((kk & 7) * 32 + (c & 31)) * 2; }
; DI int v_rd_base(int lane) { return ((lane & 3) << 3) | (((lane >> 2) & 3) << 6) | (((lane >> 4) & 1) << 5) | (((lane >> 5) & 1) << 8); }
; template <int OFF> DI s16x4 tr_read(int vb) { s16x4 r; asm volatile("ds_read_b64_tr_b16 %0, %1 offset:%2" : "=&v"(r) : "v"(vb), "i"(OFF) : "memory"); return r; }
; template <int D0> DI void pv_one(f32x16& od, int vb, bf16x8 pa0, bf16x8 pa1, bf16x8 pa2, bf16x8 pa3) {
;     const s16x4 l0 = tr_read<v_rd_off(D0, 0, 0)>(vb), h0 = tr_read<v_rd_off(D0, 0, 1)>(vb), l1 = tr_read<v_rd_off(D0, 1, 0)>(vb), h1 = tr_read<v_rd_off(D0, 1, 1)>(vb);
.LBB0_1064:
	v_exp_f32_e32 v64, v64
	v_exp_f32_e32 v100, v68
	v_exp_f32_e32 v68, v65
	v_exp_f32_e32 v66, v66
	v_exp_f32_e32 v96, v70
	v_exp_f32_e32 v70, v69
	v_exp_f32_e32 v69, v67
	v_add_f32_e32 v65, 0, v64
	v_add_f32_e32 v65, v68, v65
	v_add_f32_e32 v65, v66, v65
	v_exp_f32_e32 v71, v71
	v_add_f32_e32 v65, v69, v65
	v_exp_f32_e32 v72, v72
	v_add_f32_e32 v65, v100, v65
	v_exp_f32_e32 v73, v73
	v_add_f32_e32 v65, v70, v65
	v_exp_f32_e32 v74, v74
	v_add_f32_e32 v65, v96, v65
	v_exp_f32_e32 v75, v75
	v_add_f32_e32 v65, v71, v65
	v_exp_f32_e32 v76, v76
	v_add_f32_e32 v65, v72, v65
	v_exp_f32_e32 v77, v77
	v_add_f32_e32 v65, v73, v65
	v_exp_f32_e32 v78, v78
	v_add_f32_e32 v65, v74, v65
	v_exp_f32_e32 v79, v79
	v_add_f32_e32 v65, v75, v65
	v_exp_f32_e32 v80, v80
	v_add_f32_e32 v65, v76, v65
	v_exp_f32_e32 v81, v81
	v_add_f32_e32 v65, v77, v65
	v_exp_f32_e32 v82, v82
	v_add_f32_e32 v65, v78, v65
	v_exp_f32_e32 v83, v83
	v_add_f32_e32 v65, v79, v65
	v_exp_f32_e32 v84, v84
	v_add_f32_e32 v65, v80, v65
	v_exp_f32_e32 v85, v85
	v_add_f32_e32 v65, v81, v65
	v_exp_f32_e32 v86, v86
	v_add_f32_e32 v65, v82, v65
	v_exp_f32_e32 v87, v87
	v_add_f32_e32 v65, v83, v65
	v_exp_f32_e32 v88, v88
	v_add_f32_e32 v65, v84, v65
	v_exp_f32_e32 v89, v89
	v_add_f32_e32 v65, v85, v65
	v_exp_f32_e32 v90, v90
	v_add_f32_e32 v65, v86, v65
	v_exp_f32_e32 v91, v91
	v_add_f32_e32 v65, v87, v65
	v_exp_f32_e32 v92, v92
	v_add_f32_e32 v65, v88, v65
	v_exp_f32_e32 v93, v93
	v_add_f32_e32 v65, v89, v65
	v_exp_f32_e32 v94, v94
	v_add_f32_e32 v65, v90, v65
	v_exp_f32_e32 v95, v95
	v_add_f32_e32 v65, v91, v65
	v_add_f32_e32 v65, v92, v65
	v_add_f32_e32 v65, v93, v65
	v_add_f32_e32 v65, v94, v65
	v_add_f32_e32 v65, v95, v65
	v_mov_b32_e32 v67, v65
	v_cvt_pk_bf16_f32 v68, v64, v68
	v_cvt_pk_bf16_f32 v69, v66, v69
	v_cvt_pk_bf16_f32 v70, v100, v70
	v_cvt_pk_bf16_f32 v71, v96, v71
	s_nop 1
	v_permlane32_swap_b32_e32 v65, v67
	v_cvt_pk_bf16_f32 v72, v72, v73
	v_cvt_pk_bf16_f32 v73, v74, v75
	v_cvt_pk_bf16_f32 v74, v76, v77
	v_cvt_pk_bf16_f32 v75, v78, v79
	v_cvt_pk_bf16_f32 v76, v80, v81
	v_cvt_pk_bf16_f32 v77, v82, v83
	v_cvt_pk_bf16_f32 v78, v84, v85
	v_cvt_pk_bf16_f32 v79, v86, v87
	v_cvt_pk_bf16_f32 v80, v88, v89
	v_cvt_pk_bf16_f32 v81, v90, v91
	v_cvt_pk_bf16_f32 v82, v92, v93
	v_cvt_pk_bf16_f32 v83, v94, v95
	s_nop 0
	ds_read_b64_tr_b16 v[84:85], v201 offset:0
	ds_read_b64_tr_b16 v[86:87], v201 offset:0x100
	ds_read_b64_tr_b16 v[88:89], v201 offset:0x1000
	ds_read_b64_tr_b16 v[90:91], v201 offset:0x1100
	ds_read_b64_tr_b16 v[92:93], v201 offset:0x2000
	ds_read_b64_tr_b16 v[94:95], v201 offset:0x2100
	ds_read_b64_tr_b16 v[100:101], v201 offset:0x3000
	ds_read_b64_tr_b16 v[102:103], v201 offset:0x3100
	s_waitcnt lgkmcnt(0)
	s_nop 0
	v_mfma_f32_32x32x16_bf16 v[48:63], v[68:71], v[84:87], v[48:63]
	ds_read_b64_tr_b16 v[84:85], v201 offset:0x200
	ds_read_b64_tr_b16 v[86:87], v201 offset:0x300
	v_mfma_f32_32x32x16_bf16 v[48:63], v[72:75], v[88:91], v[48:63]
	ds_read_b64_tr_b16 v[88:89], v201 offset:0x1200
	ds_read_b64_tr_b16 v[90:91], v201 offset:0x1300
	v_mfma_f32_32x32x16_bf16 v[48:63], v[76:79], v[92:95], v[48:63]
	ds_read_b64_tr_b16 v[92:93], v201 offset:0x2200
	ds_read_b64_tr_b16 v[94:95], v201 offset:0x2300
	v_mfma_f32_32x32x16_bf16 v[48:63], v[80:83], v[100:103], v[48:63]
	ds_read_b64_tr_b16 v[100:101], v201 offset:0x3200
	ds_read_b64_tr_b16 v[102:103], v201 offset:0x3300
	s_waitcnt lgkmcnt(0)
	v_mfma_f32_32x32x16_bf16 v[32:47], v[68:71], v[84:87], v[32:47]
	ds_read_b64_tr_b16 v[84:85], v201 offset:0x400
	ds_read_b64_tr_b16 v[86:87], v201 offset:0x500
	v_mfma_f32_32x32x16_bf16 v[32:47], v[72:75], v[88:91], v[32:47]
	ds_read_b64_tr_b16 v[88:89], v201 offset:0x1400
	ds_read_b64_tr_b16 v[90:91], v201 offset:0x1500
	v_mfma_f32_32x32x16_bf16 v[32:47], v[76:79], v[92:95], v[32:47]
	ds_read_b64_tr_b16 v[92:93], v201 offset:0x2400
	ds_read_b64_tr_b16 v[94:95], v201 offset:0x2500
	v_mfma_f32_32x32x16_bf16 v[32:47], v[80:83], v[100:103], v[32:47]
	ds_read_b64_tr_b16 v[100:101], v201 offset:0x3400
	ds_read_b64_tr_b16 v[102:103], v201 offset:0x3500
	s_waitcnt lgkmcnt(0)
	v_mfma_f32_32x32x16_bf16 v[16:31], v[68:71], v[84:87], v[16:31]
	ds_read_b64_tr_b16 v[84:85], v201 offset:0x600
	ds_read_b64_tr_b16 v[86:87], v201 offset:0x700
	v_mfma_f32_32x32x16_bf16 v[16:31], v[72:75], v[88:91], v[16:31]
	ds_read_b64_tr_b16 v[88:89], v201 offset:0x1600
	ds_read_b64_tr_b16 v[90:91], v201 offset:0x1700
	v_mfma_f32_32x32x16_bf16 v[16:31], v[76:79], v[92:95], v[16:31]
	ds_read_b64_tr_b16 v[92:93], v201 offset:0x2600
	ds_read_b64_tr_b16 v[94:95], v201 offset:0x2700
	v_mfma_f32_32x32x16_bf16 v[16:31], v[80:83], v[100:103], v[16:31]
	ds_read_b64_tr_b16 v[100:101], v201 offset:0x3600
	ds_read_b64_tr_b16 v[102:103], v201 offset:0x3700
	s_waitcnt lgkmcnt(0)
	v_mfma_f32_32x32x16_bf16 v[0:15], v[68:71], v[84:87], v[0:15]
	v_mov_b32_e32 v96, v199
	s_mov_b64 s[4:5], s[0:1]
	s_load_dwordx2 s[4:5], s[4:5], 0x110
	v_and_b32_e32 v71, 63, v96
	v_and_b32_e32 v64, 0x3fffffc0, v96
	v_mfma_f32_32x32x16_bf16 v[0:15], v[72:75], v[88:91], v[0:15]
	v_and_b32_e32 v69, 31, v96
	v_lshl_add_u32 v68, v64, 2, 0
	v_mov_b32_e32 v64, v210
	s_nop 1
	v_permlane32_swap_b32_e32 v210, v64
	v_add_f32_e32 v210, v210, v64
	v_cmp_gt_u32_e32 vcc, 32, v71
	v_mfma_f32_32x32x16_bf16 v[0:15], v[76:79], v[92:95], v[0:15]
	v_mfma_f32_32x32x16_bf16 v[0:15], v[80:83], v[100:103], v[0:15]
	s_and_saveexec_b64 s[6:7], vcc
	s_cbranch_execz .LBB0_1066
	v_mul_f32_e32 v64, v210, v112
	v_add_f32_e32 v66, v97, v98
	v_pk_add_f32 v[64:65], v[64:65], v[66:67]
	v_lshl_add_u32 v70, v69, 2, v68
	v_fmac_f32_e32 v65, v64, v99
	ds_write_b32 v70, v65 offset:49152
